# grid barrier leader path: removed the unused per-XCD relay atomic and the wait for its completion
# speedup vs baseline: 1.0063x; 1.0063x over previous
.LBB0_186:
	s_or_b64 exec, exec, s[2:3]
	s_mov_b64 s[2:3], exec
	v_mbcnt_lo_u32_b32 v0, s2, 0
	v_mbcnt_hi_u32_b32 v0, s3, v0
	v_cmp_eq_u32_e32 vcc, 0, v0
	s_waitcnt vmcnt(0)
	buffer_inv sc1
	s_and_saveexec_b64 s[6:7], vcc
	s_cbranch_execz .LBB0_188
	s_bcnt1_i32_b64 s2, s[2:3]
	v_mov_b32_e32 v0, s2
	v_mov_b32_e32 v1, 0x2000
.LBB0_188:
	s_or_b64 exec, exec, s[6:7]
	s_waitcnt vmcnt(0)

.LBB0_1208:
	s_or_b64 exec, exec, s[2:3]
	s_mov_b64 s[2:3], exec
	v_mbcnt_lo_u32_b32 v0, s2, 0
	v_mbcnt_hi_u32_b32 v0, s3, v0
	v_cmp_eq_u32_e32 vcc, 0, v0
	s_waitcnt vmcnt(0)
	buffer_inv sc1
	s_and_saveexec_b64 s[6:7], vcc
	s_cbranch_execz .LBB0_1210
	s_bcnt1_i32_b64 s2, s[2:3]
	v_mov_b32_e32 v0, s2
	v_mov_b32_e32 v1, 0x2000
.LBB0_1210:
	s_or_b64 exec, exec, s[6:7]
	s_waitcnt vmcnt(0)
